# split-K f32 partial stores (context units) non-temporal: written once at the head of the phase, read once in the next
# speedup vs baseline: 1.0045x; 1.0045x over previous
;     __device__ __forceinline__ void operator()(const f32x4 (&acc)[2][2][4][2], const Unit& u, int wr, int wc, int fr, int fq) const {
;         const int row0 = u.pm * BM + wr * 64 + fr, col0 = u.pn * BM + wc * 32 + 8 * fq;
;         float* base = CP + ((size_t)u.ks * 512 + (row0 - 8192)) * 2048 + col0;
; #pragma unroll
;         for (int ai = 0; ai < 2; ++ai)
; #pragma unroll
;             for (int m = 0; m < 4; ++m) { float* rowp = base + (size_t)(ai * HALF + m * 16) * 2048;
; #pragma unroll
;                 for (int bj = 0; bj < 2; ++bj) { *(f32x4*)(rowp + bj * HALF) = acc[ai][bj][m][0]; *(f32x4*)(rowp + bj * HALF + 4) = acc[ai][bj][m][1]; } }
;     }
.LBB0_812:
	s_and_b64 vcc, exec, s[6:7]
	s_movk_i32 s25, 0x1600
	s_movk_i32 s24, 0x410
	s_cbranch_vccnz .LBB0_800
	s_ashr_i32 s11, s10, 31
	v_lshl_add_u32 v142, s30, 8, v147
	s_lshl_b64 s[6:7], s[10:11], 22
	v_ashrrev_i32_e32 v143, 31, v142
	s_add_u32 s6, s96, s6
	v_lshl_or_b32 v140, s8, 8, v148
	s_addc_u32 s7, s97, s7
	v_lshlrev_b64 v[142:143], 13, v[142:143]
	v_lshl_add_u64 v[142:143], s[6:7], 0, v[142:143]
	v_ashrrev_i32_e32 v141, 31, v140
	v_lshl_add_u64 v[140:141], v[140:141], 2, v[142:143]
	s_mov_b32 s6, 0x20000
	global_store_dwordx4 v[140:141], v[98:101], off nt
	global_store_dwordx4 v[140:141], v[102:105], off offset:16 nt
	global_store_dwordx4 v[140:141], v[106:109], off offset:512 nt
	global_store_dwordx4 v[140:141], v[110:113], off offset:528 nt
	v_add_co_u32_e32 v98, vcc, s6, v140
	s_mov_b32 s6, 0x40000
	s_nop 0
	v_addc_co_u32_e32 v99, vcc, 0, v141, vcc
	global_store_dwordx4 v[98:99], v[126:129], off nt
	global_store_dwordx4 v[98:99], v[122:125], off offset:16 nt
	global_store_dwordx4 v[98:99], v[114:117], off offset:512 nt
	global_store_dwordx4 v[98:99], v[118:121], off offset:528 nt
	v_add_co_u32_e32 v98, vcc, s6, v140
	s_mov_b32 s6, 0x60000
	s_nop 0
	v_addc_co_u32_e32 v99, vcc, 0, v141, vcc
	global_store_dwordx4 v[98:99], v[94:97], off nt
	global_store_dwordx4 v[98:99], v[90:93], off offset:16 nt
	global_store_dwordx4 v[98:99], v[86:89], off offset:512 nt
	global_store_dwordx4 v[98:99], v[82:85], off offset:528 nt
	s_nop 1
	v_add_co_u32_e32 v82, vcc, s6, v140
	s_mov_b32 s6, 0x100000
	s_nop 0
	v_addc_co_u32_e32 v83, vcc, 0, v141, vcc
	global_store_dwordx4 v[82:83], v[78:81], off nt
	global_store_dwordx4 v[82:83], v[74:77], off offset:16 nt
	global_store_dwordx4 v[82:83], v[70:73], off offset:512 nt
	global_store_dwordx4 v[82:83], v[66:69], off offset:528 nt
	s_nop 1
	v_add_co_u32_e32 v66, vcc, s6, v140
	s_mov_b32 s6, 0x120000
	s_nop 0
	v_addc_co_u32_e32 v67, vcc, 0, v141, vcc
	global_store_dwordx4 v[66:67], v[62:65], off nt
	global_store_dwordx4 v[66:67], v[58:61], off offset:16 nt
	global_store_dwordx4 v[66:67], v[54:57], off offset:512 nt
	global_store_dwordx4 v[66:67], v[50:53], off offset:528 nt
	s_nop 1
	v_add_co_u32_e32 v50, vcc, s6, v140
	s_mov_b32 s6, 0x140000
	s_nop 0
	v_addc_co_u32_e32 v51, vcc, 0, v141, vcc
	global_store_dwordx4 v[50:51], v[46:49], off nt
	global_store_dwordx4 v[50:51], v[42:45], off offset:16 nt
	global_store_dwordx4 v[50:51], v[38:41], off offset:512 nt
	global_store_dwordx4 v[50:51], v[34:37], off offset:528 nt
	s_nop 1
	v_add_co_u32_e32 v34, vcc, s6, v140
	s_nop 1
	v_addc_co_u32_e32 v35, vcc, 0, v141, vcc
	global_store_dwordx4 v[34:35], v[30:33], off nt
	global_store_dwordx4 v[34:35], v[26:29], off offset:16 nt
	global_store_dwordx4 v[34:35], v[22:25], off offset:512 nt
	global_store_dwordx4 v[34:35], v[18:21], off offset:528 nt
	s_nop 1
	v_add_co_u32_e32 v18, vcc, 0x160000, v140
	s_nop 1
	v_addc_co_u32_e32 v19, vcc, 0, v141, vcc
	s_andn2_b64 vcc, exec, s[12:13]
	global_store_dwordx4 v[18:19], v[14:17], off nt
	global_store_dwordx4 v[18:19], v[10:13], off offset:16 nt
	global_store_dwordx4 v[18:19], v[6:9], off offset:512 nt
	global_store_dwordx4 v[18:19], v[2:5], off offset:528 nt
	s_cbranch_vccnz .LBB0_815
	s_barrier

;     __device__ __forceinline__ void operator()(const f32x4 (&acc)[2][2][4][2], const Unit& u, int wr, int wc, int fr, int fq) const {
;         const int row0 = u.pm * BM + wr * 64 + fr, col0 = u.pn * BM + wc * 32 + 8 * fq;
;         float* base = CP + ((size_t)u.ks * 512 + (row0 - 8192)) * 2048 + col0;
; #pragma unroll
;         for (int ai = 0; ai < 2; ++ai)
; #pragma unroll
;             for (int m = 0; m < 4; ++m) { float* rowp = base + (size_t)(ai * HALF + m * 16) * 2048;
; #pragma unroll
;                 for (int bj = 0; bj < 2; ++bj) { *(f32x4*)(rowp + bj * HALF) = acc[ai][bj][m][0]; *(f32x4*)(rowp + bj * HALF + 4) = acc[ai][bj][m][1]; } }
;     }
.LBB0_1800:
	v_readlane_b32 s34, v254, 40
	s_andn2_b64 vcc, exec, s[30:31]
	v_readlane_b32 s35, v254, 41
	s_cbranch_vccnz .LBB0_1792
	s_ashr_i32 s13, s12, 31
	v_lshl_add_u32 v142, s0, 8, v147
	s_lshl_b64 s[12:13], s[12:13], 22
	v_ashrrev_i32_e32 v143, 31, v142
	s_add_u32 s12, s96, s12
	v_lshl_or_b32 v140, s4, 8, v148
	s_addc_u32 s13, s97, s13
	v_lshlrev_b64 v[142:143], 13, v[142:143]
	v_lshl_add_u64 v[142:143], s[12:13], 0, v[142:143]
	v_ashrrev_i32_e32 v141, 31, v140
	v_lshl_add_u64 v[140:141], v[140:141], 2, v[142:143]
	s_mov_b32 s0, 0x20000
	global_store_dwordx4 v[140:141], v[122:125], off nt
	global_store_dwordx4 v[140:141], v[126:129], off offset:16 nt
	global_store_dwordx4 v[140:141], v[118:121], off offset:512 nt
	global_store_dwordx4 v[140:141], v[114:117], off offset:528 nt
	s_nop 1
	v_add_co_u32_e32 v114, vcc, s0, v140
	s_mov_b32 s0, 0x40000
	s_nop 0
	v_addc_co_u32_e32 v115, vcc, 0, v141, vcc
	global_store_dwordx4 v[114:115], v[110:113], off nt
	global_store_dwordx4 v[114:115], v[106:109], off offset:16 nt
	global_store_dwordx4 v[114:115], v[102:105], off offset:512 nt
	global_store_dwordx4 v[114:115], v[98:101], off offset:528 nt
	s_nop 1
	v_add_co_u32_e32 v98, vcc, s0, v140
	s_mov_b32 s0, 0x60000
	s_nop 0
	v_addc_co_u32_e32 v99, vcc, 0, v141, vcc
	global_store_dwordx4 v[98:99], v[94:97], off nt
	global_store_dwordx4 v[98:99], v[90:93], off offset:16 nt
	global_store_dwordx4 v[98:99], v[86:89], off offset:512 nt
	global_store_dwordx4 v[98:99], v[82:85], off offset:528 nt
	s_nop 1
	v_add_co_u32_e32 v82, vcc, s0, v140
	s_mov_b32 s0, 0x100000
	s_nop 0
	v_addc_co_u32_e32 v83, vcc, 0, v141, vcc
	global_store_dwordx4 v[82:83], v[78:81], off nt
	global_store_dwordx4 v[82:83], v[74:77], off offset:16 nt
	global_store_dwordx4 v[82:83], v[70:73], off offset:512 nt
	global_store_dwordx4 v[82:83], v[66:69], off offset:528 nt
	s_nop 1
	v_add_co_u32_e32 v66, vcc, s0, v140
	s_mov_b32 s0, 0x120000
	s_nop 0
	v_addc_co_u32_e32 v67, vcc, 0, v141, vcc
	global_store_dwordx4 v[66:67], v[62:65], off nt
	global_store_dwordx4 v[66:67], v[58:61], off offset:16 nt
	global_store_dwordx4 v[66:67], v[54:57], off offset:512 nt
	global_store_dwordx4 v[66:67], v[50:53], off offset:528 nt
	s_nop 1
	v_add_co_u32_e32 v50, vcc, s0, v140
	s_mov_b32 s0, 0x140000
	s_nop 0
	v_addc_co_u32_e32 v51, vcc, 0, v141, vcc
	global_store_dwordx4 v[50:51], v[46:49], off nt
	global_store_dwordx4 v[50:51], v[42:45], off offset:16 nt
	global_store_dwordx4 v[50:51], v[38:41], off offset:512 nt
	global_store_dwordx4 v[50:51], v[34:37], off offset:528 nt
	s_nop 1
	v_add_co_u32_e32 v34, vcc, s0, v140
	s_nop 1
	v_addc_co_u32_e32 v35, vcc, 0, v141, vcc
	global_store_dwordx4 v[34:35], v[30:33], off nt
	global_store_dwordx4 v[34:35], v[26:29], off offset:16 nt
	global_store_dwordx4 v[34:35], v[22:25], off offset:512 nt
	global_store_dwordx4 v[34:35], v[18:21], off offset:528 nt
	s_nop 1
	v_add_co_u32_e32 v18, vcc, 0x160000, v140
	s_nop 1
	v_addc_co_u32_e32 v19, vcc, 0, v141, vcc
	s_andn2_b64 vcc, exec, s[8:9]
	global_store_dwordx4 v[18:19], v[14:17], off nt
	global_store_dwordx4 v[18:19], v[10:13], off offset:16 nt
	global_store_dwordx4 v[18:19], v[6:9], off offset:512 nt
	global_store_dwordx4 v[18:19], v[2:5], off offset:528 nt
	s_cbranch_vccnz .LBB0_1803
	s_barrier

;     __device__ __forceinline__ void operator()(const f32x4 (&acc)[2][2][4][2], const Unit& u, int wr, int wc, int fr, int fq) const {
;         const int row0 = u.pm * BM + wr * 64 + fr, col0 = u.pn * BM + wc * 32 + 8 * fq;
;         float* base = CP + ((size_t)u.ks * 512 + (row0 - 8192)) * 2048 + col0;
; #pragma unroll
;         for (int ai = 0; ai < 2; ++ai)
; #pragma unroll
;             for (int m = 0; m < 4; ++m) { float* rowp = base + (size_t)(ai * HALF + m * 16) * 2048;
; #pragma unroll
;                 for (int bj = 0; bj < 2; ++bj) { *(f32x4*)(rowp + bj * HALF) = acc[ai][bj][m][0]; *(f32x4*)(rowp + bj * HALF + 4) = acc[ai][bj][m][1]; } }
;     }
.LBB0_2331:
	v_readlane_b32 s34, v254, 40
	s_and_b64 vcc, exec, s[6:7]
	v_readlane_b32 s35, v254, 41
	s_cbranch_vccnz .LBB0_2319
	s_ashr_i32 s21, s20, 31
	v_lshl_add_u32 v142, s48, 8, v148
	s_lshl_b64 s[6:7], s[20:21], 22
	v_ashrrev_i32_e32 v143, 31, v142
	s_add_u32 s6, s96, s6
	v_lshl_or_b32 v140, s10, 8, v149
	s_addc_u32 s7, s97, s7
	v_lshlrev_b64 v[142:143], 13, v[142:143]
	v_lshl_add_u64 v[142:143], s[6:7], 0, v[142:143]
	v_ashrrev_i32_e32 v141, 31, v140
	v_lshl_add_u64 v[140:141], v[140:141], 2, v[142:143]
	s_mov_b32 s6, 0x20000
	global_store_dwordx4 v[140:141], v[126:129], off nt
	global_store_dwordx4 v[140:141], v[122:125], off offset:16 nt
	global_store_dwordx4 v[140:141], v[118:121], off offset:512 nt
	global_store_dwordx4 v[140:141], v[114:117], off offset:528 nt
	s_nop 1
	v_add_co_u32_e32 v114, vcc, s6, v140
	s_mov_b32 s6, 0x40000
	s_nop 0
	v_addc_co_u32_e32 v115, vcc, 0, v141, vcc
	global_store_dwordx4 v[114:115], v[110:113], off nt
	global_store_dwordx4 v[114:115], v[106:109], off offset:16 nt
	global_store_dwordx4 v[114:115], v[102:105], off offset:512 nt
	global_store_dwordx4 v[114:115], v[98:101], off offset:528 nt
	s_nop 1
	v_add_co_u32_e32 v98, vcc, s6, v140
	s_mov_b32 s6, 0x60000
	s_nop 0
	v_addc_co_u32_e32 v99, vcc, 0, v141, vcc
	global_store_dwordx4 v[98:99], v[94:97], off nt
	global_store_dwordx4 v[98:99], v[90:93], off offset:16 nt
	global_store_dwordx4 v[98:99], v[86:89], off offset:512 nt
	global_store_dwordx4 v[98:99], v[82:85], off offset:528 nt
	s_nop 1
	v_add_co_u32_e32 v82, vcc, s6, v140
	s_mov_b32 s6, 0x100000
	s_nop 0
	v_addc_co_u32_e32 v83, vcc, 0, v141, vcc
	global_store_dwordx4 v[82:83], v[78:81], off nt
	global_store_dwordx4 v[82:83], v[74:77], off offset:16 nt
	global_store_dwordx4 v[82:83], v[70:73], off offset:512 nt
	global_store_dwordx4 v[82:83], v[66:69], off offset:528 nt
	s_nop 1
	v_add_co_u32_e32 v66, vcc, s6, v140
	s_mov_b32 s6, 0x120000
	s_nop 0
	v_addc_co_u32_e32 v67, vcc, 0, v141, vcc
	global_store_dwordx4 v[66:67], v[62:65], off nt
	global_store_dwordx4 v[66:67], v[58:61], off offset:16 nt
	global_store_dwordx4 v[66:67], v[54:57], off offset:512 nt
	global_store_dwordx4 v[66:67], v[50:53], off offset:528 nt
	s_nop 1
	v_add_co_u32_e32 v50, vcc, s6, v140
	s_mov_b32 s6, 0x140000
	s_nop 0
	v_addc_co_u32_e32 v51, vcc, 0, v141, vcc
	global_store_dwordx4 v[50:51], v[46:49], off nt
	global_store_dwordx4 v[50:51], v[42:45], off offset:16 nt
	global_store_dwordx4 v[50:51], v[38:41], off offset:512 nt
	global_store_dwordx4 v[50:51], v[34:37], off offset:528 nt
	s_nop 1
	v_add_co_u32_e32 v34, vcc, s6, v140
	s_nop 1
	v_addc_co_u32_e32 v35, vcc, 0, v141, vcc
	global_store_dwordx4 v[34:35], v[30:33], off nt
	global_store_dwordx4 v[34:35], v[26:29], off offset:16 nt
	global_store_dwordx4 v[34:35], v[22:25], off offset:512 nt
	global_store_dwordx4 v[34:35], v[18:21], off offset:528 nt
	s_nop 1
	v_add_co_u32_e32 v18, vcc, 0x160000, v140
	s_nop 1
	v_addc_co_u32_e32 v19, vcc, 0, v141, vcc
	s_andn2_b64 vcc, exec, s[16:17]
	global_store_dwordx4 v[18:19], v[14:17], off nt
	global_store_dwordx4 v[18:19], v[10:13], off offset:16 nt
	global_store_dwordx4 v[18:19], v[6:9], off offset:512 nt
	global_store_dwordx4 v[18:19], v[2:5], off offset:528 nt
	s_cbranch_vccnz .LBB0_2334
	s_barrier
